# final-layer residual epilogue (h + acc -> d_out with pad-row removal) also coalesced through the per-wave LDS transpose with pipelined h loads
# baseline (speedup 1.0000x reference)
.Lres_fin:
	v_lshrrev_b32_e32 v145, 6, v154
	v_bfe_u32 v146, v163, 5, 2
	v_lshl_add_u32 v145, v145, 2, v146
	v_mul_u32_u24_e32 v145, 2304, v145
	v_add_u32_e32 v145, 135424, v145
	v_and_b32_e32 v146, 15, v189
	v_mul_u32_u24_e32 v146, 144, v146
	v_lshrrev_b32_e32 v147, 4, v189
	v_lshl_add_u32 v146, v147, 5, v146
	v_add_u32_e32 v152, v145, v146
	v_lshrrev_b32_e32 v146, 3, v189
	v_and_b32_e32 v147, 7, v189
	v_mul_u32_u24_e32 v153, 144, v146
	v_lshl_add_u32 v153, v147, 4, v153
	v_add_u32_e32 v153, v145, v153
	v_and_b32_e32 v148, 0xfffffff0, v154
	v_add_u32_e32 v148, v148, v146
	v_lshl_add_u32 v149, s23, 8, v148
	v_and_b32_e32 v148, 0x60, v163
	v_lshl_add_u32 v148, s22, 8, v148
	v_lshl_add_u32 v150, v147, 2, v148
	v_lshlrev_b32_e32 v145, 12, v149
	v_lshl_add_u32 v144, v150, 2, v145
	v_add_u32_e32 v150, 0xfffe0000, v150
	v_mov_b32_e32 v145, v144
	v_add_u32_e32 v146, 0x8000, v144
	global_load_dwordx4 v[192:195], v145, s[72:73]
	global_load_dwordx4 v[196:199], v146, s[72:73]
	v_add_u32_e32 v147, 0x200, v144
	v_add_u32_e32 v148, 0x8200, v144
	global_load_dwordx4 v[200:203], v147, s[72:73]
	global_load_dwordx4 v[204:207], v148, s[72:73]
	v_add_u32_e32 v145, 0x10000, v144
	v_add_u32_e32 v146, 0x18000, v144
	global_load_dwordx4 v[208:211], v145, s[72:73]
	global_load_dwordx4 v[212:215], v146, s[72:73]
	v_add_u32_e32 v147, 0x10200, v144
	v_add_u32_e32 v148, 0x18200, v144
	global_load_dwordx4 v[216:219], v147, s[72:73]
	global_load_dwordx4 v[220:223], v148, s[72:73]
	ds_write_b128 v152, v[126:129]
	ds_write_b128 v152, v[122:125] offset:16
	ds_read_b128 v[240:243], v153
	ds_read_b128 v[244:247], v153 offset:1152
	ds_write_b128 v152, v[118:121]
	ds_write_b128 v152, v[114:117] offset:16
	ds_read_b128 v[130:133], v153
	ds_read_b128 v[176:179], v153 offset:1152
	s_waitcnt lgkmcnt(4)
	s_waitcnt vmcnt(6)
	v_pk_add_f32 v[240:241], v[240:241], v[192:193]
	v_pk_add_f32 v[242:243], v[242:243], v[194:195]
	v_pk_add_f32 v[244:245], v[244:245], v[196:197]
	v_pk_add_f32 v[246:247], v[246:247], v[198:199]
	v_mov_b32_e32 v171, v149
	v_mul_hi_i32 v170, v171, s74
	v_lshrrev_b32_e32 v151, 31, v170
	v_ashrrev_i32_e32 v170, 12, v170
	v_add_u32_e32 v170, v170, v151
	v_mad_i32_i24 v171, v170, s76, v171
	v_cmp_lt_i32_e64 s[18:19], s77, v171
	v_lshlrev_b32_e32 v170, 23, v170
	v_lshl_add_u32 v170, v171, 10, v170
	v_add_u32_e32 v170, v170, v150
	v_lshlrev_b32_e32 v170, 2, v170
	v_add_u32_e32 v181, 8, v149
	v_mul_hi_i32 v180, v181, s74
	v_lshrrev_b32_e32 v248, 31, v180
	v_ashrrev_i32_e32 v180, 12, v180
	v_add_u32_e32 v180, v180, v248
	v_mad_i32_i24 v181, v180, s76, v181
	v_cmp_lt_i32_e64 s[20:21], s77, v181
	v_lshlrev_b32_e32 v180, 23, v180
	v_lshl_add_u32 v180, v181, 10, v180
	v_add_u32_e32 v180, v180, v150
	v_lshlrev_b32_e32 v180, 2, v180
	s_mov_b64 exec, s[18:19]
	global_store_dwordx4 v170, v[240:243], s[68:69] nt
	s_mov_b64 exec, s[20:21]
	global_store_dwordx4 v180, v[244:247], s[68:69] nt
	s_mov_b64 exec, -1
	v_add_u32_e32 v145, 0x20000, v144
	v_add_u32_e32 v146, 0x28000, v144
	global_load_dwordx4 v[192:195], v145, s[72:73]
	global_load_dwordx4 v[196:199], v146, s[72:73]
	v_add_u32_e32 v147, 0x20200, v144
	v_add_u32_e32 v148, 0x28200, v144
	global_load_dwordx4 v[126:129], v147, s[72:73]
	global_load_dwordx4 v[122:125], v148, s[72:73]
	ds_write_b128 v152, v[108:111]
	ds_write_b128 v152, v[104:107] offset:16
	ds_read_b128 v[240:243], v153
	ds_read_b128 v[244:247], v153 offset:1152
	s_waitcnt lgkmcnt(4)
	s_waitcnt vmcnt(10)
	v_pk_add_f32 v[130:131], v[130:131], v[200:201]
	v_pk_add_f32 v[132:133], v[132:133], v[202:203]
	v_pk_add_f32 v[176:177], v[176:177], v[204:205]
	v_pk_add_f32 v[178:179], v[178:179], v[206:207]
	v_mov_b32_e32 v171, v149
	v_mul_hi_i32 v170, v171, s74
	v_lshrrev_b32_e32 v151, 31, v170
	v_ashrrev_i32_e32 v170, 12, v170
	v_add_u32_e32 v170, v170, v151
	v_mad_i32_i24 v171, v170, s76, v171
	v_cmp_lt_i32_e64 s[18:19], s77, v171
	v_lshlrev_b32_e32 v170, 23, v170
	v_lshl_add_u32 v170, v171, 10, v170
	v_add_u32_e32 v170, v170, v150
	v_add_u32_e32 v170, 128, v170
	v_lshlrev_b32_e32 v170, 2, v170
	v_add_u32_e32 v181, 8, v149
	v_mul_hi_i32 v180, v181, s74
	v_lshrrev_b32_e32 v248, 31, v180
	v_ashrrev_i32_e32 v180, 12, v180
	v_add_u32_e32 v180, v180, v248
	v_mad_i32_i24 v181, v180, s76, v181
	v_cmp_lt_i32_e64 s[20:21], s77, v181
	v_lshlrev_b32_e32 v180, 23, v180
	v_lshl_add_u32 v180, v181, 10, v180
	v_add_u32_e32 v180, v180, v150
	v_add_u32_e32 v180, 128, v180
	v_lshlrev_b32_e32 v180, 2, v180
	s_mov_b64 exec, s[18:19]
	global_store_dwordx4 v170, v[130:133], s[68:69] nt
	s_mov_b64 exec, s[20:21]
	global_store_dwordx4 v180, v[176:179], s[68:69] nt
	s_mov_b64 exec, -1
	v_add_u32_e32 v145, 0x30000, v144
	v_add_u32_e32 v146, 0x38000, v144
	global_load_dwordx4 v[200:203], v145, s[72:73]
	global_load_dwordx4 v[204:207], v146, s[72:73]
	v_add_u32_e32 v147, 0x30200, v144
	v_add_u32_e32 v148, 0x38200, v144
	global_load_dwordx4 v[118:121], v147, s[72:73]
	global_load_dwordx4 v[114:117], v148, s[72:73]
	ds_write_b128 v152, v[100:103]
	ds_write_b128 v152, v[96:99] offset:16
	ds_read_b128 v[130:133], v153
	ds_read_b128 v[176:179], v153 offset:1152
	s_waitcnt lgkmcnt(4)
	s_waitcnt vmcnt(14)
	v_pk_add_f32 v[240:241], v[240:241], v[208:209]
	v_pk_add_f32 v[242:243], v[242:243], v[210:211]
	v_pk_add_f32 v[244:245], v[244:245], v[212:213]
	v_pk_add_f32 v[246:247], v[246:247], v[214:215]
	v_add_u32_e32 v171, 16, v149
	v_mul_hi_i32 v170, v171, s74
	v_lshrrev_b32_e32 v151, 31, v170
	v_ashrrev_i32_e32 v170, 12, v170
	v_add_u32_e32 v170, v170, v151
	v_mad_i32_i24 v171, v170, s76, v171
	v_cmp_lt_i32_e64 s[18:19], s77, v171
	v_lshlrev_b32_e32 v170, 23, v170
	v_lshl_add_u32 v170, v171, 10, v170
	v_add_u32_e32 v170, v170, v150
	v_lshlrev_b32_e32 v170, 2, v170
	v_add_u32_e32 v181, 24, v149
	v_mul_hi_i32 v180, v181, s74
	v_lshrrev_b32_e32 v248, 31, v180
	v_ashrrev_i32_e32 v180, 12, v180
	v_add_u32_e32 v180, v180, v248
	v_mad_i32_i24 v181, v180, s76, v181
	v_cmp_lt_i32_e64 s[20:21], s77, v181
	v_lshlrev_b32_e32 v180, 23, v180
	v_lshl_add_u32 v180, v181, 10, v180
	v_add_u32_e32 v180, v180, v150
	v_lshlrev_b32_e32 v180, 2, v180
	s_mov_b64 exec, s[18:19]
	global_store_dwordx4 v170, v[240:243], s[68:69] nt
	s_mov_b64 exec, s[20:21]
	global_store_dwordx4 v180, v[244:247], s[68:69] nt
	s_mov_b64 exec, -1
	v_add_u32_e32 v145, 0x80000, v144
	v_add_u32_e32 v146, 0x88000, v144
	global_load_dwordx4 v[208:211], v145, s[72:73]
	global_load_dwordx4 v[212:215], v146, s[72:73]
	v_add_u32_e32 v147, 0x80200, v144
	v_add_u32_e32 v148, 0x88200, v144
	global_load_dwordx4 v[108:111], v147, s[72:73]
	global_load_dwordx4 v[104:107], v148, s[72:73]
	ds_write_b128 v152, v[92:95]
	ds_write_b128 v152, v[88:91] offset:16
	ds_read_b128 v[240:243], v153
	ds_read_b128 v[244:247], v153 offset:1152
	s_waitcnt lgkmcnt(4)
	s_waitcnt vmcnt(18)
	v_pk_add_f32 v[130:131], v[130:131], v[216:217]
	v_pk_add_f32 v[132:133], v[132:133], v[218:219]
	v_pk_add_f32 v[176:177], v[176:177], v[220:221]
	v_pk_add_f32 v[178:179], v[178:179], v[222:223]
	v_add_u32_e32 v171, 16, v149
	v_mul_hi_i32 v170, v171, s74
	v_lshrrev_b32_e32 v151, 31, v170
	v_ashrrev_i32_e32 v170, 12, v170
	v_add_u32_e32 v170, v170, v151
	v_mad_i32_i24 v171, v170, s76, v171
	v_cmp_lt_i32_e64 s[18:19], s77, v171
	v_lshlrev_b32_e32 v170, 23, v170
	v_lshl_add_u32 v170, v171, 10, v170
	v_add_u32_e32 v170, v170, v150
	v_add_u32_e32 v170, 128, v170
	v_lshlrev_b32_e32 v170, 2, v170
	v_add_u32_e32 v181, 24, v149
	v_mul_hi_i32 v180, v181, s74
	v_lshrrev_b32_e32 v248, 31, v180
	v_ashrrev_i32_e32 v180, 12, v180
	v_add_u32_e32 v180, v180, v248
	v_mad_i32_i24 v181, v180, s76, v181
	v_cmp_lt_i32_e64 s[20:21], s77, v181
	v_lshlrev_b32_e32 v180, 23, v180
	v_lshl_add_u32 v180, v181, 10, v180
	v_add_u32_e32 v180, v180, v150
	v_add_u32_e32 v180, 128, v180
	v_lshlrev_b32_e32 v180, 2, v180
	s_mov_b64 exec, s[18:19]
	global_store_dwordx4 v170, v[130:133], s[68:69] nt
	s_mov_b64 exec, s[20:21]
	global_store_dwordx4 v180, v[176:179], s[68:69] nt
	s_mov_b64 exec, -1
	v_add_u32_e32 v145, 0x90000, v144
	v_add_u32_e32 v146, 0x98000, v144
	global_load_dwordx4 v[216:219], v145, s[72:73]
	global_load_dwordx4 v[220:223], v146, s[72:73]
	v_add_u32_e32 v147, 0x90200, v144
	v_add_u32_e32 v148, 0x98200, v144
	global_load_dwordx4 v[100:103], v147, s[72:73]
	global_load_dwordx4 v[96:99], v148, s[72:73]
	ds_write_b128 v152, v[84:87]
	ds_write_b128 v152, v[80:83] offset:16
	ds_read_b128 v[130:133], v153
	ds_read_b128 v[176:179], v153 offset:1152
	s_waitcnt lgkmcnt(4)
	s_waitcnt vmcnt(20)
	v_pk_add_f32 v[240:241], v[240:241], v[192:193]
	v_pk_add_f32 v[242:243], v[242:243], v[194:195]
	v_pk_add_f32 v[244:245], v[244:245], v[196:197]
	v_pk_add_f32 v[246:247], v[246:247], v[198:199]
	v_add_u32_e32 v171, 32, v149
	v_mul_hi_i32 v170, v171, s74
	v_lshrrev_b32_e32 v151, 31, v170
	v_ashrrev_i32_e32 v170, 12, v170
	v_add_u32_e32 v170, v170, v151
	v_mad_i32_i24 v171, v170, s76, v171
	v_cmp_lt_i32_e64 s[18:19], s77, v171
	v_lshlrev_b32_e32 v170, 23, v170
	v_lshl_add_u32 v170, v171, 10, v170
	v_add_u32_e32 v170, v170, v150
	v_lshlrev_b32_e32 v170, 2, v170
	v_add_u32_e32 v181, 40, v149
	v_mul_hi_i32 v180, v181, s74
	v_lshrrev_b32_e32 v248, 31, v180
	v_ashrrev_i32_e32 v180, 12, v180
	v_add_u32_e32 v180, v180, v248
	v_mad_i32_i24 v181, v180, s76, v181
	v_cmp_lt_i32_e64 s[20:21], s77, v181
	v_lshlrev_b32_e32 v180, 23, v180
	v_lshl_add_u32 v180, v181, 10, v180
	v_add_u32_e32 v180, v180, v150
	v_lshlrev_b32_e32 v180, 2, v180
	s_mov_b64 exec, s[18:19]
	global_store_dwordx4 v170, v[240:243], s[68:69] nt
	s_mov_b64 exec, s[20:21]
	global_store_dwordx4 v180, v[244:247], s[68:69] nt
	s_mov_b64 exec, -1
	v_add_u32_e32 v145, 0xa0000, v144
	v_add_u32_e32 v146, 0xa8000, v144
	global_load_dwordx4 v[192:195], v145, s[72:73]
	global_load_dwordx4 v[196:199], v146, s[72:73]
	v_add_u32_e32 v147, 0xa0200, v144
	v_add_u32_e32 v148, 0xa8200, v144
	global_load_dwordx4 v[92:95], v147, s[72:73]
	global_load_dwordx4 v[88:91], v148, s[72:73]
	ds_write_b128 v152, v[76:79]
	ds_write_b128 v152, v[72:75] offset:16
	ds_read_b128 v[240:243], v153
	ds_read_b128 v[244:247], v153 offset:1152
	s_waitcnt lgkmcnt(4)
	s_waitcnt vmcnt(24)
	v_pk_add_f32 v[130:131], v[130:131], v[126:127]
	v_pk_add_f32 v[132:133], v[132:133], v[128:129]
	v_pk_add_f32 v[176:177], v[176:177], v[122:123]
	v_pk_add_f32 v[178:179], v[178:179], v[124:125]
	v_add_u32_e32 v171, 32, v149
	v_mul_hi_i32 v170, v171, s74
	v_lshrrev_b32_e32 v151, 31, v170
	v_ashrrev_i32_e32 v170, 12, v170
	v_add_u32_e32 v170, v170, v151
	v_mad_i32_i24 v171, v170, s76, v171
	v_cmp_lt_i32_e64 s[18:19], s77, v171
	v_lshlrev_b32_e32 v170, 23, v170
	v_lshl_add_u32 v170, v171, 10, v170
	v_add_u32_e32 v170, v170, v150
	v_add_u32_e32 v170, 128, v170
	v_lshlrev_b32_e32 v170, 2, v170
	v_add_u32_e32 v181, 40, v149
	v_mul_hi_i32 v180, v181, s74
	v_lshrrev_b32_e32 v248, 31, v180
	v_ashrrev_i32_e32 v180, 12, v180
	v_add_u32_e32 v180, v180, v248
	v_mad_i32_i24 v181, v180, s76, v181
	v_cmp_lt_i32_e64 s[20:21], s77, v181
	v_lshlrev_b32_e32 v180, 23, v180
	v_lshl_add_u32 v180, v181, 10, v180
	v_add_u32_e32 v180, v180, v150
	v_add_u32_e32 v180, 128, v180
	v_lshlrev_b32_e32 v180, 2, v180
	s_mov_b64 exec, s[18:19]
	global_store_dwordx4 v170, v[130:133], s[68:69] nt
	s_mov_b64 exec, s[20:21]
	global_store_dwordx4 v180, v[176:179], s[68:69] nt
	s_mov_b64 exec, -1
	v_add_u32_e32 v145, 0xb0000, v144
	v_add_u32_e32 v146, 0xb8000, v144
	global_load_dwordx4 v[126:129], v145, s[72:73]
	global_load_dwordx4 v[122:125], v146, s[72:73]
	v_add_u32_e32 v147, 0xb0200, v144
	v_add_u32_e32 v148, 0xb8200, v144
	global_load_dwordx4 v[84:87], v147, s[72:73]
	global_load_dwordx4 v[80:83], v148, s[72:73]
	ds_write_b128 v152, v[68:71]
	ds_write_b128 v152, v[64:67] offset:16
	ds_read_b128 v[130:133], v153
	ds_read_b128 v[176:179], v153 offset:1152
	s_waitcnt lgkmcnt(4)
	s_waitcnt vmcnt(26)
	v_pk_add_f32 v[240:241], v[240:241], v[200:201]
	v_pk_add_f32 v[242:243], v[242:243], v[202:203]
	v_pk_add_f32 v[244:245], v[244:245], v[204:205]
	v_pk_add_f32 v[246:247], v[246:247], v[206:207]
	v_add_u32_e32 v171, 48, v149
	v_mul_hi_i32 v170, v171, s74
	v_lshrrev_b32_e32 v151, 31, v170
	v_ashrrev_i32_e32 v170, 12, v170
	v_add_u32_e32 v170, v170, v151
	v_mad_i32_i24 v171, v170, s76, v171
	v_cmp_lt_i32_e64 s[18:19], s77, v171
	v_lshlrev_b32_e32 v170, 23, v170
	v_lshl_add_u32 v170, v171, 10, v170
	v_add_u32_e32 v170, v170, v150
	v_lshlrev_b32_e32 v170, 2, v170
	v_add_u32_e32 v181, 56, v149
	v_mul_hi_i32 v180, v181, s74
	v_lshrrev_b32_e32 v248, 31, v180
	v_ashrrev_i32_e32 v180, 12, v180
	v_add_u32_e32 v180, v180, v248
	v_mad_i32_i24 v181, v180, s76, v181
	v_cmp_lt_i32_e64 s[20:21], s77, v181
	v_lshlrev_b32_e32 v180, 23, v180
	v_lshl_add_u32 v180, v181, 10, v180
	v_add_u32_e32 v180, v180, v150
	v_lshlrev_b32_e32 v180, 2, v180
	s_mov_b64 exec, s[18:19]
	global_store_dwordx4 v170, v[240:243], s[68:69] nt
	s_mov_b64 exec, s[20:21]
	global_store_dwordx4 v180, v[244:247], s[68:69] nt
	s_mov_b64 exec, -1
	ds_write_b128 v152, v[60:63]
	ds_write_b128 v152, v[56:59] offset:16
	ds_read_b128 v[240:243], v153
	ds_read_b128 v[244:247], v153 offset:1152
	s_waitcnt lgkmcnt(4)
	s_waitcnt vmcnt(26)
	v_pk_add_f32 v[130:131], v[130:131], v[118:119]
	v_pk_add_f32 v[132:133], v[132:133], v[120:121]
	v_pk_add_f32 v[176:177], v[176:177], v[114:115]
	v_pk_add_f32 v[178:179], v[178:179], v[116:117]
	v_add_u32_e32 v171, 48, v149
	v_mul_hi_i32 v170, v171, s74
	v_lshrrev_b32_e32 v151, 31, v170
	v_ashrrev_i32_e32 v170, 12, v170
	v_add_u32_e32 v170, v170, v151
	v_mad_i32_i24 v171, v170, s76, v171
	v_cmp_lt_i32_e64 s[18:19], s77, v171
	v_lshlrev_b32_e32 v170, 23, v170
	v_lshl_add_u32 v170, v171, 10, v170
	v_add_u32_e32 v170, v170, v150
	v_add_u32_e32 v170, 128, v170
	v_lshlrev_b32_e32 v170, 2, v170
	v_add_u32_e32 v181, 56, v149
	v_mul_hi_i32 v180, v181, s74
	v_lshrrev_b32_e32 v248, 31, v180
	v_ashrrev_i32_e32 v180, 12, v180
	v_add_u32_e32 v180, v180, v248
	v_mad_i32_i24 v181, v180, s76, v181
	v_cmp_lt_i32_e64 s[20:21], s77, v181
	v_lshlrev_b32_e32 v180, 23, v180
	v_lshl_add_u32 v180, v181, 10, v180
	v_add_u32_e32 v180, v180, v150
	v_add_u32_e32 v180, 128, v180
	v_lshlrev_b32_e32 v180, 2, v180
	s_mov_b64 exec, s[18:19]
	global_store_dwordx4 v170, v[130:133], s[68:69] nt
	s_mov_b64 exec, s[20:21]
	global_store_dwordx4 v180, v[176:179], s[68:69] nt
	s_mov_b64 exec, -1
	ds_write_b128 v152, v[52:55]
	ds_write_b128 v152, v[48:51] offset:16
	ds_read_b128 v[130:133], v153
	ds_read_b128 v[176:179], v153 offset:1152
	s_waitcnt lgkmcnt(4)
	s_waitcnt vmcnt(24)
	v_pk_add_f32 v[240:241], v[240:241], v[208:209]
	v_pk_add_f32 v[242:243], v[242:243], v[210:211]
	v_pk_add_f32 v[244:245], v[244:245], v[212:213]
	v_pk_add_f32 v[246:247], v[246:247], v[214:215]
	v_add_u32_e32 v171, 128, v149
	v_mul_hi_i32 v170, v171, s74
	v_lshrrev_b32_e32 v151, 31, v170
	v_ashrrev_i32_e32 v170, 12, v170
	v_add_u32_e32 v170, v170, v151
	v_mad_i32_i24 v171, v170, s76, v171
	v_cmp_lt_i32_e64 s[18:19], s77, v171
	v_lshlrev_b32_e32 v170, 23, v170
	v_lshl_add_u32 v170, v171, 10, v170
	v_add_u32_e32 v170, v170, v150
	v_lshlrev_b32_e32 v170, 2, v170
	v_add_u32_e32 v181, 136, v149
	v_mul_hi_i32 v180, v181, s74
	v_lshrrev_b32_e32 v248, 31, v180
	v_ashrrev_i32_e32 v180, 12, v180
	v_add_u32_e32 v180, v180, v248
	v_mad_i32_i24 v181, v180, s76, v181
	v_cmp_lt_i32_e64 s[20:21], s77, v181
	v_lshlrev_b32_e32 v180, 23, v180
	v_lshl_add_u32 v180, v181, 10, v180
	v_add_u32_e32 v180, v180, v150
	v_lshlrev_b32_e32 v180, 2, v180
	s_mov_b64 exec, s[18:19]
	global_store_dwordx4 v170, v[240:243], s[68:69] nt
	s_mov_b64 exec, s[20:21]
	global_store_dwordx4 v180, v[244:247], s[68:69] nt
	s_mov_b64 exec, -1
	ds_write_b128 v152, v[44:47]
	ds_write_b128 v152, v[40:43] offset:16
	ds_read_b128 v[240:243], v153
	ds_read_b128 v[244:247], v153 offset:1152
	s_waitcnt lgkmcnt(4)
	s_waitcnt vmcnt(24)
	v_pk_add_f32 v[130:131], v[130:131], v[108:109]
	v_pk_add_f32 v[132:133], v[132:133], v[110:111]
	v_pk_add_f32 v[176:177], v[176:177], v[104:105]
	v_pk_add_f32 v[178:179], v[178:179], v[106:107]
	v_add_u32_e32 v171, 128, v149
	v_mul_hi_i32 v170, v171, s74
	v_lshrrev_b32_e32 v151, 31, v170
	v_ashrrev_i32_e32 v170, 12, v170
	v_add_u32_e32 v170, v170, v151
	v_mad_i32_i24 v171, v170, s76, v171
	v_cmp_lt_i32_e64 s[18:19], s77, v171
	v_lshlrev_b32_e32 v170, 23, v170
	v_lshl_add_u32 v170, v171, 10, v170
	v_add_u32_e32 v170, v170, v150
	v_add_u32_e32 v170, 128, v170
	v_lshlrev_b32_e32 v170, 2, v170
	v_add_u32_e32 v181, 136, v149
	v_mul_hi_i32 v180, v181, s74
	v_lshrrev_b32_e32 v248, 31, v180
	v_ashrrev_i32_e32 v180, 12, v180
	v_add_u32_e32 v180, v180, v248
	v_mad_i32_i24 v181, v180, s76, v181
	v_cmp_lt_i32_e64 s[20:21], s77, v181
	v_lshlrev_b32_e32 v180, 23, v180
	v_lshl_add_u32 v180, v181, 10, v180
	v_add_u32_e32 v180, v180, v150
	v_add_u32_e32 v180, 128, v180
	v_lshlrev_b32_e32 v180, 2, v180
	s_mov_b64 exec, s[18:19]
	global_store_dwordx4 v170, v[130:133], s[68:69] nt
	s_mov_b64 exec, s[20:21]
	global_store_dwordx4 v180, v[176:179], s[68:69] nt
	s_mov_b64 exec, -1
	ds_write_b128 v152, v[36:39]
	ds_write_b128 v152, v[32:35] offset:16
	ds_read_b128 v[130:133], v153
	ds_read_b128 v[176:179], v153 offset:1152
	s_waitcnt lgkmcnt(4)
	s_waitcnt vmcnt(22)
	v_pk_add_f32 v[240:241], v[240:241], v[216:217]
	v_pk_add_f32 v[242:243], v[242:243], v[218:219]
	v_pk_add_f32 v[244:245], v[244:245], v[220:221]
	v_pk_add_f32 v[246:247], v[246:247], v[222:223]
	v_add_u32_e32 v171, 144, v149
	v_mul_hi_i32 v170, v171, s74
	v_lshrrev_b32_e32 v151, 31, v170
	v_ashrrev_i32_e32 v170, 12, v170
	v_add_u32_e32 v170, v170, v151
	v_mad_i32_i24 v171, v170, s76, v171
	v_cmp_lt_i32_e64 s[18:19], s77, v171
	v_lshlrev_b32_e32 v170, 23, v170
	v_lshl_add_u32 v170, v171, 10, v170
	v_add_u32_e32 v170, v170, v150
	v_lshlrev_b32_e32 v170, 2, v170
	v_add_u32_e32 v181, 152, v149
	v_mul_hi_i32 v180, v181, s74
	v_lshrrev_b32_e32 v248, 31, v180
	v_ashrrev_i32_e32 v180, 12, v180
	v_add_u32_e32 v180, v180, v248
	v_mad_i32_i24 v181, v180, s76, v181
	v_cmp_lt_i32_e64 s[20:21], s77, v181
	v_lshlrev_b32_e32 v180, 23, v180
	v_lshl_add_u32 v180, v181, 10, v180
	v_add_u32_e32 v180, v180, v150
	v_lshlrev_b32_e32 v180, 2, v180
	s_mov_b64 exec, s[18:19]
	global_store_dwordx4 v170, v[240:243], s[68:69] nt
	s_mov_b64 exec, s[20:21]
	global_store_dwordx4 v180, v[244:247], s[68:69] nt
	s_mov_b64 exec, -1
	ds_write_b128 v152, v[28:31]
	ds_write_b128 v152, v[24:27] offset:16
	ds_read_b128 v[240:243], v153
	ds_read_b128 v[244:247], v153 offset:1152
	s_waitcnt lgkmcnt(4)
	s_waitcnt vmcnt(22)
	v_pk_add_f32 v[130:131], v[130:131], v[100:101]
	v_pk_add_f32 v[132:133], v[132:133], v[102:103]
	v_pk_add_f32 v[176:177], v[176:177], v[96:97]
	v_pk_add_f32 v[178:179], v[178:179], v[98:99]
	v_add_u32_e32 v171, 144, v149
	v_mul_hi_i32 v170, v171, s74
	v_lshrrev_b32_e32 v151, 31, v170
	v_ashrrev_i32_e32 v170, 12, v170
	v_add_u32_e32 v170, v170, v151
	v_mad_i32_i24 v171, v170, s76, v171
	v_cmp_lt_i32_e64 s[18:19], s77, v171
	v_lshlrev_b32_e32 v170, 23, v170
	v_lshl_add_u32 v170, v171, 10, v170
	v_add_u32_e32 v170, v170, v150
	v_add_u32_e32 v170, 128, v170
	v_lshlrev_b32_e32 v170, 2, v170
	v_add_u32_e32 v181, 152, v149
	v_mul_hi_i32 v180, v181, s74
	v_lshrrev_b32_e32 v248, 31, v180
	v_ashrrev_i32_e32 v180, 12, v180
	v_add_u32_e32 v180, v180, v248
	v_mad_i32_i24 v181, v180, s76, v181
	v_cmp_lt_i32_e64 s[20:21], s77, v181
	v_lshlrev_b32_e32 v180, 23, v180
	v_lshl_add_u32 v180, v181, 10, v180
	v_add_u32_e32 v180, v180, v150
	v_add_u32_e32 v180, 128, v180
	v_lshlrev_b32_e32 v180, 2, v180
	s_mov_b64 exec, s[18:19]
	global_store_dwordx4 v170, v[130:133], s[68:69] nt
	s_mov_b64 exec, s[20:21]
	global_store_dwordx4 v180, v[176:179], s[68:69] nt
	s_mov_b64 exec, -1
	ds_write_b128 v152, v[20:23]
	ds_write_b128 v152, v[16:19] offset:16
	ds_read_b128 v[130:133], v153
	ds_read_b128 v[176:179], v153 offset:1152
	s_waitcnt lgkmcnt(4)
	s_waitcnt vmcnt(20)
	v_pk_add_f32 v[240:241], v[240:241], v[192:193]
	v_pk_add_f32 v[242:243], v[242:243], v[194:195]
	v_pk_add_f32 v[244:245], v[244:245], v[196:197]
	v_pk_add_f32 v[246:247], v[246:247], v[198:199]
	v_add_u32_e32 v171, 160, v149
	v_mul_hi_i32 v170, v171, s74
	v_lshrrev_b32_e32 v151, 31, v170
	v_ashrrev_i32_e32 v170, 12, v170
	v_add_u32_e32 v170, v170, v151
	v_mad_i32_i24 v171, v170, s76, v171
	v_cmp_lt_i32_e64 s[18:19], s77, v171
	v_lshlrev_b32_e32 v170, 23, v170
	v_lshl_add_u32 v170, v171, 10, v170
	v_add_u32_e32 v170, v170, v150
	v_lshlrev_b32_e32 v170, 2, v170
	v_add_u32_e32 v181, 168, v149
	v_mul_hi_i32 v180, v181, s74
	v_lshrrev_b32_e32 v248, 31, v180
	v_ashrrev_i32_e32 v180, 12, v180
	v_add_u32_e32 v180, v180, v248
	v_mad_i32_i24 v181, v180, s76, v181
	v_cmp_lt_i32_e64 s[20:21], s77, v181
	v_lshlrev_b32_e32 v180, 23, v180
	v_lshl_add_u32 v180, v181, 10, v180
	v_add_u32_e32 v180, v180, v150
	v_lshlrev_b32_e32 v180, 2, v180
	s_mov_b64 exec, s[18:19]
	global_store_dwordx4 v170, v[240:243], s[68:69] nt
	s_mov_b64 exec, s[20:21]
	global_store_dwordx4 v180, v[244:247], s[68:69] nt
	s_mov_b64 exec, -1
	ds_write_b128 v152, v[12:15]
	ds_write_b128 v152, v[8:11] offset:16
	ds_read_b128 v[240:243], v153
	ds_read_b128 v[244:247], v153 offset:1152
	s_waitcnt lgkmcnt(4)
	s_waitcnt vmcnt(20)
	v_pk_add_f32 v[130:131], v[130:131], v[92:93]
	v_pk_add_f32 v[132:133], v[132:133], v[94:95]
	v_pk_add_f32 v[176:177], v[176:177], v[88:89]
	v_pk_add_f32 v[178:179], v[178:179], v[90:91]
	v_add_u32_e32 v171, 160, v149
	v_mul_hi_i32 v170, v171, s74
	v_lshrrev_b32_e32 v151, 31, v170
	v_ashrrev_i32_e32 v170, 12, v170
	v_add_u32_e32 v170, v170, v151
	v_mad_i32_i24 v171, v170, s76, v171
	v_cmp_lt_i32_e64 s[18:19], s77, v171
	v_lshlrev_b32_e32 v170, 23, v170
	v_lshl_add_u32 v170, v171, 10, v170
	v_add_u32_e32 v170, v170, v150
	v_add_u32_e32 v170, 128, v170
	v_lshlrev_b32_e32 v170, 2, v170
	v_add_u32_e32 v181, 168, v149
	v_mul_hi_i32 v180, v181, s74
	v_lshrrev_b32_e32 v248, 31, v180
	v_ashrrev_i32_e32 v180, 12, v180
	v_add_u32_e32 v180, v180, v248
	v_mad_i32_i24 v181, v180, s76, v181
	v_cmp_lt_i32_e64 s[20:21], s77, v181
	v_lshlrev_b32_e32 v180, 23, v180
	v_lshl_add_u32 v180, v181, 10, v180
	v_add_u32_e32 v180, v180, v150
	v_add_u32_e32 v180, 128, v180
	v_lshlrev_b32_e32 v180, 2, v180
	s_mov_b64 exec, s[18:19]
	global_store_dwordx4 v170, v[130:133], s[68:69] nt
	s_mov_b64 exec, s[20:21]
	global_store_dwordx4 v180, v[176:179], s[68:69] nt
	s_mov_b64 exec, -1
	ds_write_b128 v152, v[4:7]
	ds_write_b128 v152, v[0:3] offset:16
	ds_read_b128 v[130:133], v153
	ds_read_b128 v[176:179], v153 offset:1152
	s_waitcnt lgkmcnt(4)
	s_waitcnt vmcnt(18)
	v_pk_add_f32 v[240:241], v[240:241], v[126:127]
	v_pk_add_f32 v[242:243], v[242:243], v[128:129]
	v_pk_add_f32 v[244:245], v[244:245], v[122:123]
	v_pk_add_f32 v[246:247], v[246:247], v[124:125]
	v_add_u32_e32 v171, 176, v149
	v_mul_hi_i32 v170, v171, s74
	v_lshrrev_b32_e32 v151, 31, v170
	v_ashrrev_i32_e32 v170, 12, v170
	v_add_u32_e32 v170, v170, v151
	v_mad_i32_i24 v171, v170, s76, v171
	v_cmp_lt_i32_e64 s[18:19], s77, v171
	v_lshlrev_b32_e32 v170, 23, v170
	v_lshl_add_u32 v170, v171, 10, v170
	v_add_u32_e32 v170, v170, v150
	v_lshlrev_b32_e32 v170, 2, v170
	v_add_u32_e32 v181, 184, v149
	v_mul_hi_i32 v180, v181, s74
	v_lshrrev_b32_e32 v248, 31, v180
	v_ashrrev_i32_e32 v180, 12, v180
	v_add_u32_e32 v180, v180, v248
	v_mad_i32_i24 v181, v180, s76, v181
	v_cmp_lt_i32_e64 s[20:21], s77, v181
	v_lshlrev_b32_e32 v180, 23, v180
	v_lshl_add_u32 v180, v181, 10, v180
	v_add_u32_e32 v180, v180, v150
	v_lshlrev_b32_e32 v180, 2, v180
	s_mov_b64 exec, s[18:19]
	global_store_dwordx4 v170, v[240:243], s[68:69] nt
	s_mov_b64 exec, s[20:21]
	global_store_dwordx4 v180, v[244:247], s[68:69] nt
	s_mov_b64 exec, -1
	s_waitcnt lgkmcnt(0)
	s_waitcnt vmcnt(18)
	v_pk_add_f32 v[130:131], v[130:131], v[84:85]
	v_pk_add_f32 v[132:133], v[132:133], v[86:87]
	v_pk_add_f32 v[176:177], v[176:177], v[80:81]
	v_pk_add_f32 v[178:179], v[178:179], v[82:83]
	v_add_u32_e32 v171, 176, v149
	v_mul_hi_i32 v170, v171, s74
	v_lshrrev_b32_e32 v151, 31, v170
	v_ashrrev_i32_e32 v170, 12, v170
	v_add_u32_e32 v170, v170, v151
	v_mad_i32_i24 v171, v170, s76, v171
	v_cmp_lt_i32_e64 s[18:19], s77, v171
	v_lshlrev_b32_e32 v170, 23, v170
	v_lshl_add_u32 v170, v171, 10, v170
	v_add_u32_e32 v170, v170, v150
	v_add_u32_e32 v170, 128, v170
	v_lshlrev_b32_e32 v170, 2, v170
	v_add_u32_e32 v181, 184, v149
	v_mul_hi_i32 v180, v181, s74
	v_lshrrev_b32_e32 v248, 31, v180
	v_ashrrev_i32_e32 v180, 12, v180
	v_add_u32_e32 v180, v180, v248
	v_mad_i32_i24 v181, v180, s76, v181
	v_cmp_lt_i32_e64 s[20:21], s77, v181
	v_lshlrev_b32_e32 v180, 23, v180
	v_lshl_add_u32 v180, v181, 10, v180
	v_add_u32_e32 v180, v180, v150
	v_add_u32_e32 v180, 128, v180
	v_lshlrev_b32_e32 v180, 2, v180
	s_mov_b64 exec, s[18:19]
	global_store_dwordx4 v170, v[130:133], s[68:69] nt
	s_mov_b64 exec, s[20:21]
	global_store_dwordx4 v180, v[176:179], s[68:69] nt
	s_mov_b64 exec, -1
	s_branch .Lres_join
